# FFN-down epilogue: both bf16 residual quads of a row group requested right behind its statistics loads (groups 2-8), no waits behind the first half's stores
# baseline (speedup 1.0000x reference)
; DI float bperm(float v, int srclane) { return __int_as_float(__builtin_amdgcn_ds_bpermute(srclane << 2, __float_as_int(v))); }
; DI u32x4 pack8(const float (&v)[8]) { u32x4 w; w.x = pk2(v[0], v[1]); w.y = pk2(v[2], v[3]); w.z = pk2(v[4], v[5]); w.w = pk2(v[6], v[7]); return w; }
; DI void row_stats(const float* STAT, int row, int fq, int lane, float& mu, float& rstd) {
;     const f32x4 a = *(const f32x4*)(STAT + (size_t)row * 32 + fq * 8), b = *(const f32x4*)(STAT + (size_t)row * 32 + fq * 8 + 4);
;     float s = (a[0] + a[2]) + (b[0] + b[2]), q = (a[1] + a[3]) + (b[1] + b[3]);
;     s += bperm(s, lane ^ 16); q += bperm(q, lane ^ 16); s += bperm(s, lane ^ 32); q += bperm(q, lane ^ 32);
;     mu = s * (1.0f / 1024.0f); rstd = __builtin_amdgcn_rsqf(fmaxf(q * (1.0f / 1024.0f) - mu * mu, 0.f) + EPS);
;     DI void operator()(const f32x4 (&acc)[2][2][4][2], const pg8::Unit& u, int wr, int wc, int fr, int fq) const {
;     ...
;             for (int m = 0; m < 4; ++m) { const int row = row0 + ai * 128 + m * 16; const size_t off = (size_t)row * DMODEL + col0; float mu, rstd; row_stats(STAT, row, fq, lane, mu, rstd);
; #pragma unroll
;                 for (int bj = 0; bj < 2; ++bj) { float p[8]; unpack8(*(const u32x4*)(XBin + off + bj * 128), p);
;                     const f32x4 g0 = *(const f32x4*)(g + col0 + bj * 128), g1 = *(const f32x4*)(g + col0 + bj * 128 + 4), b0 = *(const f32x4*)(b + col0 + bj * 128), b1 = *(const f32x4*)(b + col0 + bj * 128 + 4);
;                     float o[8];
; #pragma unroll
;                     for (int k = 0; k < 8; ++k) { const float gg = k < 4 ? g0[k & 3] : g1[k & 3], bb = k < 4 ? b0[k & 3] : b1[k & 3]; const float x1 = (p[k] - mu) * rstd * gg + bb; o[k] = x1 * ALPHA + acc[ai][bj][m][k >> 2][k & 3]; }
;                     if (out32) { *(f32x4*)(out32 + off + bj * 128) = (f32x4){o[0], o[1], o[2], o[3]}; *(f32x4*)(out32 + off + bj * 128 + 4) = (f32x4){o[4], o[5], o[6], o[7]}; }
;                     else *(u32x4*)(XBout + off + bj * 128) = pack8(o); }
.LBB0_1987:
	s_nop 0
	v_add_u32_e32 v114, 16, v146
	v_ashrrev_i32_e32 v115, 31, v114
	v_lshlrev_b64 v[116:117], 10, v[114:115]
	v_lshlrev_b64 v[114:115], 7, v[114:115]
	v_lshl_add_u64 v[114:115], s[36:37], 0, v[114:115]
	v_lshl_add_u64 v[118:119], v[144:145], 2, v[114:115]
	s_nop 1
	v_mov_b32_e32 v122, v220
	v_mov_b32_e32 v123, v221
	v_mov_b32_e32 v124, v222
	v_mov_b32_e32 v125, v223
	v_mov_b32_e32 v126, v224
	v_mov_b32_e32 v127, v225
	v_mov_b32_e32 v128, v226
	v_mov_b32_e32 v129, v227
	v_mov_b32_e32 v150, v228
	v_mov_b32_e32 v151, v229
	v_mov_b32_e32 v152, v230
	v_mov_b32_e32 v153, v231
	v_mov_b32_e32 v154, v232
	v_mov_b32_e32 v155, v233
	v_mov_b32_e32 v156, v234
	v_mov_b32_e32 v157, v235
	v_lshl_add_u64 v[120:121], v[116:117], 0, v[148:149]
	global_load_dwordx4 v[114:117], v[118:119], off offset:16
	global_load_dwordx4 v[164:167], v[118:119], off
	v_lshl_add_u64 v[178:179], v[120:121], 1, s[26:27]
	global_load_dwordx4 v[170:173], v[178:179], off
	global_load_dwordx4 v[174:177], v[178:179], off offset:256
	s_mov_b32 s2, 0x3a800000
	s_and_b64 vcc, exec, s[18:19]
	s_waitcnt vmcnt(3)
	v_pk_add_f32 v[114:115], v[114:115], v[116:117]
	s_waitcnt vmcnt(2)
	v_pk_add_f32 v[118:119], v[164:165], v[166:167]
	s_nop 0
	v_pk_add_f32 v[114:115], v[118:119], v[114:115]
	ds_bpermute_b32 v116, v163, v114
	ds_bpermute_b32 v117, v163, v115
	s_waitcnt lgkmcnt(0)
	v_pk_add_f32 v[114:115], v[114:115], v[116:117]
	ds_bpermute_b32 v116, v162, v114
	ds_bpermute_b32 v117, v162, v115
	s_waitcnt lgkmcnt(0)
	v_pk_add_f32 v[114:115], v[114:115], v[116:117]
	s_nop 0
	v_pk_mul_f32 v[116:117], v[114:115], s[2:3] op_sel_hi:[1,0]
	s_nop 0
	v_fma_f32 v114, -v116, v116, v117
	v_max_f32_e32 v114, 0, v114
	v_add_f32_e32 v114, 0x3727c5ac, v114
	v_rsq_f32_e32 v118, v114
	v_lshl_add_u64 v[114:115], v[120:121], 1, s[26:27]
	s_waitcnt vmcnt(0)
	v_mov_b32_e32 v164, v170
	v_mov_b32_e32 v165, v171
	v_mov_b32_e32 v166, v172
	v_mov_b32_e32 v167, v173
	v_lshl_add_u64 v[120:121], v[120:121], 2, s[28:29]
	s_waitcnt vmcnt(0)
	v_lshlrev_b32_e32 v168, 16, v164
	v_and_b32_e32 v169, 0xffff0000, v164
	v_pk_add_f32 v[168:169], v[168:169], v[116:117] op_sel_hi:[1,0] neg_lo:[0,1] neg_hi:[0,1]
	s_nop 0
	v_pk_mul_f32 v[168:169], v[168:169], v[118:119] op_sel_hi:[1,0]
	s_nop 0
	v_pk_fma_f32 v[126:127], v[126:127], v[168:169], v[154:155]
	s_nop 0
	v_pk_fma_f32 v[110:111], v[126:127], s[86:87], v[110:111] op_sel_hi:[1,0,1]
	v_lshlrev_b32_e32 v126, 16, v165
	v_and_b32_e32 v127, 0xffff0000, v165
	v_pk_add_f32 v[126:127], v[126:127], v[116:117] op_sel_hi:[1,0] neg_lo:[0,1] neg_hi:[0,1]
	s_nop 0
	v_pk_mul_f32 v[126:127], v[126:127], v[118:119] op_sel_hi:[1,0]
	s_nop 0
	v_pk_fma_f32 v[126:127], v[128:129], v[126:127], v[156:157]
	s_nop 0
	v_pk_fma_f32 v[112:113], v[126:127], s[86:87], v[112:113] op_sel_hi:[1,0,1]
	v_lshlrev_b32_e32 v126, 16, v166
	v_and_b32_e32 v127, 0xffff0000, v166
	v_pk_add_f32 v[126:127], v[126:127], v[116:117] op_sel_hi:[1,0] neg_lo:[0,1] neg_hi:[0,1]
	s_nop 0
	v_pk_mul_f32 v[126:127], v[126:127], v[118:119] op_sel_hi:[1,0]
	s_nop 0
	v_pk_fma_f32 v[122:123], v[122:123], v[126:127], v[150:151]
	s_nop 0
	v_pk_fma_f32 v[106:107], v[122:123], s[86:87], v[106:107] op_sel_hi:[1,0,1]
	v_lshlrev_b32_e32 v122, 16, v167
	v_and_b32_e32 v123, 0xffff0000, v167
	v_pk_add_f32 v[122:123], v[122:123], v[116:117] op_sel_hi:[1,0] neg_lo:[0,1] neg_hi:[0,1]
	s_nop 0
	v_pk_mul_f32 v[122:123], v[122:123], v[118:119] op_sel_hi:[1,0]
	s_nop 0
	v_pk_fma_f32 v[122:123], v[124:125], v[122:123], v[152:153]
	s_nop 0
	v_pk_fma_f32 v[108:109], v[122:123], s[86:87], v[108:109] op_sel_hi:[1,0,1]
	s_cbranch_vccnz .LBB0_2033
	global_store_dwordx4 v[120:121], v[110:113], off
	global_store_dwordx4 v[120:121], v[106:109], off offset:16
	s_cbranch_execnz .LBB0_1990

; DI u32x4 pack8(const float (&v)[8]) { u32x4 w; w.x = pk2(v[0], v[1]); w.y = pk2(v[2], v[3]); w.z = pk2(v[4], v[5]); w.w = pk2(v[6], v[7]); return w; }
;     DI void operator()(const f32x4 (&acc)[2][2][4][2], const pg8::Unit& u, int wr, int wc, int fr, int fq) const {
;     ...
;                 for (int bj = 0; bj < 2; ++bj) { float p[8]; unpack8(*(const u32x4*)(XBin + off + bj * 128), p);
;                     const f32x4 g0 = *(const f32x4*)(g + col0 + bj * 128), g1 = *(const f32x4*)(g + col0 + bj * 128 + 4), b0 = *(const f32x4*)(b + col0 + bj * 128), b1 = *(const f32x4*)(b + col0 + bj * 128 + 4);
;                     float o[8];
; #pragma unroll
;                     for (int k = 0; k < 8; ++k) { const float gg = k < 4 ? g0[k & 3] : g1[k & 3], bb = k < 4 ? b0[k & 3] : b1[k & 3]; const float x1 = (p[k] - mu) * rstd * gg + bb; o[k] = x1 * ALPHA + acc[ai][bj][m][k >> 2][k & 3]; }
;                     if (out32) { *(f32x4*)(out32 + off + bj * 128) = (f32x4){o[0], o[1], o[2], o[3]}; *(f32x4*)(out32 + off + bj * 128 + 4) = (f32x4){o[4], o[5], o[6], o[7]}; }
;                     else *(u32x4*)(XBout + off + bj * 128) = pack8(o); }
.LBB0_1990:
	s_nop 1
	v_mov_b32_e32 v106, v174
	v_mov_b32_e32 v107, v175
	v_mov_b32_e32 v108, v176
	v_mov_b32_e32 v109, v177
	s_nop 0
	s_nop 1
	v_mov_b32_e32 v110, v242
	v_mov_b32_e32 v111, v243
	v_mov_b32_e32 v112, v244
	v_mov_b32_e32 v113, v245
	v_mov_b32_e32 v122, v246
	v_mov_b32_e32 v123, v247
	v_mov_b32_e32 v124, v248
	v_mov_b32_e32 v125, v249
	v_mov_b32_e32 v126, v250
	v_mov_b32_e32 v127, v251
	v_mov_b32_e32 v128, v252
	v_mov_b32_e32 v129, v253
	v_mov_b32_e32 v150, v186
	v_mov_b32_e32 v151, v187
	v_mov_b32_e32 v152, v196
	v_mov_b32_e32 v153, v197
	v_mov_b32_e32 v117, v116
	v_mov_b32_e32 v119, v118
	s_and_b64 vcc, exec, s[18:19]
	s_nop 0
	v_lshlrev_b32_e32 v154, 16, v106
	v_and_b32_e32 v155, 0xffff0000, v106
	v_lshlrev_b32_e32 v106, 16, v107
	v_and_b32_e32 v107, 0xffff0000, v107
	v_pk_add_f32 v[106:107], v[106:107], v[116:117] neg_lo:[0,1] neg_hi:[0,1]
	v_pk_add_f32 v[154:155], v[154:155], v[116:117] neg_lo:[0,1] neg_hi:[0,1]
	v_pk_mul_f32 v[106:107], v[118:119], v[106:107]
	v_pk_mul_f32 v[154:155], v[118:119], v[154:155]
	s_nop 0
	v_pk_fma_f32 v[106:107], v[124:125], v[106:107], v[152:153]
	v_pk_fma_f32 v[122:123], v[122:123], v[154:155], v[150:151]
	v_pk_fma_f32 v[104:105], v[106:107], s[86:87], v[104:105] op_sel_hi:[1,0,1]
	v_lshlrev_b32_e32 v106, 16, v108
	v_and_b32_e32 v107, 0xffff0000, v108
	v_pk_add_f32 v[106:107], v[106:107], v[116:117] neg_lo:[0,1] neg_hi:[0,1]
	v_pk_fma_f32 v[102:103], v[122:123], s[86:87], v[102:103] op_sel_hi:[1,0,1]
	v_pk_mul_f32 v[106:107], v[118:119], v[106:107]
	s_nop 0
	v_pk_fma_f32 v[106:107], v[110:111], v[106:107], v[126:127]
	s_nop 0
	v_pk_fma_f32 v[98:99], v[106:107], s[86:87], v[98:99] op_sel_hi:[1,0,1]
	v_lshlrev_b32_e32 v106, 16, v109
	v_and_b32_e32 v107, 0xffff0000, v109
	v_pk_add_f32 v[106:107], v[106:107], v[116:117] neg_lo:[0,1] neg_hi:[0,1]
	s_nop 0
	v_pk_mul_f32 v[106:107], v[118:119], v[106:107]
	s_nop 0
	v_pk_fma_f32 v[106:107], v[112:113], v[106:107], v[128:129]
	s_nop 0
	v_pk_fma_f32 v[100:101], v[106:107], s[86:87], v[100:101] op_sel_hi:[1,0,1]
	s_cbranch_vccnz .LBB0_2034
	global_store_dwordx4 v[120:121], v[102:105], off offset:512
	global_store_dwordx4 v[120:121], v[98:101], off offset:528
	s_cbranch_execnz .LBB0_1993

; DI float bperm(float v, int srclane) { return __int_as_float(__builtin_amdgcn_ds_bpermute(srclane << 2, __float_as_int(v))); }
; DI u32x4 pack8(const float (&v)[8]) { u32x4 w; w.x = pk2(v[0], v[1]); w.y = pk2(v[2], v[3]); w.z = pk2(v[4], v[5]); w.w = pk2(v[6], v[7]); return w; }
; DI void row_stats(const float* STAT, int row, int fq, int lane, float& mu, float& rstd) {
;     const f32x4 a = *(const f32x4*)(STAT + (size_t)row * 32 + fq * 8), b = *(const f32x4*)(STAT + (size_t)row * 32 + fq * 8 + 4);
;     float s = (a[0] + a[2]) + (b[0] + b[2]), q = (a[1] + a[3]) + (b[1] + b[3]);
;     s += bperm(s, lane ^ 16); q += bperm(q, lane ^ 16); s += bperm(s, lane ^ 32); q += bperm(q, lane ^ 32);
;     mu = s * (1.0f / 1024.0f); rstd = __builtin_amdgcn_rsqf(fmaxf(q * (1.0f / 1024.0f) - mu * mu, 0.f) + EPS);
;     DI void operator()(const f32x4 (&acc)[2][2][4][2], const pg8::Unit& u, int wr, int wc, int fr, int fq) const {
;     ...
;             for (int m = 0; m < 4; ++m) { const int row = row0 + ai * 128 + m * 16; const size_t off = (size_t)row * DMODEL + col0; float mu, rstd; row_stats(STAT, row, fq, lane, mu, rstd);
; #pragma unroll
;                 for (int bj = 0; bj < 2; ++bj) { float p[8]; unpack8(*(const u32x4*)(XBin + off + bj * 128), p);
;                     const f32x4 g0 = *(const f32x4*)(g + col0 + bj * 128), g1 = *(const f32x4*)(g + col0 + bj * 128 + 4), b0 = *(const f32x4*)(b + col0 + bj * 128), b1 = *(const f32x4*)(b + col0 + bj * 128 + 4);
;                     float o[8];
; #pragma unroll
;                     for (int k = 0; k < 8; ++k) { const float gg = k < 4 ? g0[k & 3] : g1[k & 3], bb = k < 4 ? b0[k & 3] : b1[k & 3]; const float x1 = (p[k] - mu) * rstd * gg + bb; o[k] = x1 * ALPHA + acc[ai][bj][m][k >> 2][k & 3]; }
;                     if (out32) { *(f32x4*)(out32 + off + bj * 128) = (f32x4){o[0], o[1], o[2], o[3]}; *(f32x4*)(out32 + off + bj * 128 + 4) = (f32x4){o[4], o[5], o[6], o[7]}; }
;                     else *(u32x4*)(XBout + off + bj * 128) = pack8(o); }
.LBB0_1993:
	s_nop 0
	v_add_u32_e32 v98, 32, v146
	v_ashrrev_i32_e32 v99, 31, v98
	v_lshlrev_b64 v[100:101], 10, v[98:99]
	v_lshlrev_b64 v[98:99], 7, v[98:99]
	v_lshl_add_u64 v[98:99], s[36:37], 0, v[98:99]
	v_lshl_add_u64 v[102:103], v[144:145], 2, v[98:99]
	s_nop 1
	v_mov_b32_e32 v106, v220
	v_mov_b32_e32 v107, v221
	v_mov_b32_e32 v108, v222
	v_mov_b32_e32 v109, v223
	v_mov_b32_e32 v110, v224
	v_mov_b32_e32 v111, v225
	v_mov_b32_e32 v112, v226
	v_mov_b32_e32 v113, v227
	v_mov_b32_e32 v114, v228
	v_mov_b32_e32 v115, v229
	v_mov_b32_e32 v116, v230
	v_mov_b32_e32 v117, v231
	v_mov_b32_e32 v118, v232
	v_mov_b32_e32 v119, v233
	v_mov_b32_e32 v120, v234
	v_mov_b32_e32 v121, v235
	v_lshl_add_u64 v[104:105], v[100:101], 0, v[148:149]
	global_load_dwordx4 v[98:101], v[102:103], off offset:16
	global_load_dwordx4 v[122:125], v[102:103], off
	v_lshl_add_u64 v[178:179], v[104:105], 1, s[26:27]
	global_load_dwordx4 v[170:173], v[178:179], off
	global_load_dwordx4 v[174:177], v[178:179], off offset:256
	s_mov_b32 s2, 0x3a800000
	s_and_b64 vcc, exec, s[18:19]
	s_waitcnt vmcnt(3)
	v_pk_add_f32 v[98:99], v[98:99], v[100:101]
	s_waitcnt vmcnt(2)
	v_pk_add_f32 v[102:103], v[122:123], v[124:125]
	s_nop 0
	v_pk_add_f32 v[98:99], v[102:103], v[98:99]
	ds_bpermute_b32 v100, v163, v98
	ds_bpermute_b32 v101, v163, v99
	s_waitcnt lgkmcnt(0)
	v_pk_add_f32 v[98:99], v[98:99], v[100:101]
	ds_bpermute_b32 v100, v162, v98
	ds_bpermute_b32 v101, v162, v99
	s_waitcnt lgkmcnt(0)
	v_pk_add_f32 v[98:99], v[98:99], v[100:101]
	s_nop 0
	v_pk_mul_f32 v[100:101], v[98:99], s[2:3] op_sel_hi:[1,0]
	s_nop 0
	v_fma_f32 v98, -v100, v100, v101
	v_max_f32_e32 v98, 0, v98
	v_add_f32_e32 v98, 0x3727c5ac, v98
	v_rsq_f32_e32 v102, v98
	v_lshl_add_u64 v[98:99], v[104:105], 1, s[26:27]
	s_waitcnt vmcnt(0)
	v_mov_b32_e32 v122, v170
	v_mov_b32_e32 v123, v171
	v_mov_b32_e32 v124, v172
	v_mov_b32_e32 v125, v173
	v_lshl_add_u64 v[104:105], v[104:105], 2, s[28:29]
	s_waitcnt vmcnt(0)
	v_lshlrev_b32_e32 v126, 16, v122
	v_and_b32_e32 v127, 0xffff0000, v122
	v_pk_add_f32 v[126:127], v[126:127], v[100:101] op_sel_hi:[1,0] neg_lo:[0,1] neg_hi:[0,1]
	s_nop 0
	v_pk_mul_f32 v[126:127], v[126:127], v[102:103] op_sel_hi:[1,0]
	s_nop 0
	v_pk_fma_f32 v[110:111], v[110:111], v[126:127], v[118:119]
	s_nop 0
	v_pk_fma_f32 v[94:95], v[110:111], s[86:87], v[94:95] op_sel_hi:[1,0,1]
	v_lshlrev_b32_e32 v110, 16, v123
	v_and_b32_e32 v111, 0xffff0000, v123
	v_pk_add_f32 v[110:111], v[110:111], v[100:101] op_sel_hi:[1,0] neg_lo:[0,1] neg_hi:[0,1]
	s_nop 0
	v_pk_mul_f32 v[110:111], v[110:111], v[102:103] op_sel_hi:[1,0]
	s_nop 0
	v_pk_fma_f32 v[110:111], v[112:113], v[110:111], v[120:121]
	s_nop 0
	v_pk_fma_f32 v[96:97], v[110:111], s[86:87], v[96:97] op_sel_hi:[1,0,1]
	v_lshlrev_b32_e32 v110, 16, v124
	v_and_b32_e32 v111, 0xffff0000, v124
	v_pk_add_f32 v[110:111], v[110:111], v[100:101] op_sel_hi:[1,0] neg_lo:[0,1] neg_hi:[0,1]
	s_nop 0
	v_pk_mul_f32 v[110:111], v[110:111], v[102:103] op_sel_hi:[1,0]
	s_nop 0
	v_pk_fma_f32 v[106:107], v[106:107], v[110:111], v[114:115]
	s_nop 0
	v_pk_fma_f32 v[90:91], v[106:107], s[86:87], v[90:91] op_sel_hi:[1,0,1]
	v_lshlrev_b32_e32 v106, 16, v125
	v_and_b32_e32 v107, 0xffff0000, v125
	v_pk_add_f32 v[106:107], v[106:107], v[100:101] op_sel_hi:[1,0] neg_lo:[0,1] neg_hi:[0,1]
	s_nop 0
	v_pk_mul_f32 v[106:107], v[106:107], v[102:103] op_sel_hi:[1,0]
	s_nop 0
	v_pk_fma_f32 v[106:107], v[108:109], v[106:107], v[116:117]
	s_nop 0
	v_pk_fma_f32 v[92:93], v[106:107], s[86:87], v[92:93] op_sel_hi:[1,0,1]
	s_cbranch_vccnz .LBB0_2035
	global_store_dwordx4 v[104:105], v[94:97], off
	global_store_dwordx4 v[104:105], v[90:93], off offset:16
	s_cbranch_execnz .LBB0_1996

; DI u32x4 pack8(const float (&v)[8]) { u32x4 w; w.x = pk2(v[0], v[1]); w.y = pk2(v[2], v[3]); w.z = pk2(v[4], v[5]); w.w = pk2(v[6], v[7]); return w; }
;     DI void operator()(const f32x4 (&acc)[2][2][4][2], const pg8::Unit& u, int wr, int wc, int fr, int fq) const {
;     ...
;                 for (int bj = 0; bj < 2; ++bj) { float p[8]; unpack8(*(const u32x4*)(XBin + off + bj * 128), p);
;                     const f32x4 g0 = *(const f32x4*)(g + col0 + bj * 128), g1 = *(const f32x4*)(g + col0 + bj * 128 + 4), b0 = *(const f32x4*)(b + col0 + bj * 128), b1 = *(const f32x4*)(b + col0 + bj * 128 + 4);
;                     float o[8];
; #pragma unroll
;                     for (int k = 0; k < 8; ++k) { const float gg = k < 4 ? g0[k & 3] : g1[k & 3], bb = k < 4 ? b0[k & 3] : b1[k & 3]; const float x1 = (p[k] - mu) * rstd * gg + bb; o[k] = x1 * ALPHA + acc[ai][bj][m][k >> 2][k & 3]; }
;                     if (out32) { *(f32x4*)(out32 + off + bj * 128) = (f32x4){o[0], o[1], o[2], o[3]}; *(f32x4*)(out32 + off + bj * 128 + 4) = (f32x4){o[4], o[5], o[6], o[7]}; }
;                     else *(u32x4*)(XBout + off + bj * 128) = pack8(o); }
.LBB0_1996:
	s_nop 1
	v_mov_b32_e32 v90, v174
	v_mov_b32_e32 v91, v175
	v_mov_b32_e32 v92, v176
	v_mov_b32_e32 v93, v177
	s_nop 0
	s_nop 1
	v_mov_b32_e32 v94, v242
	v_mov_b32_e32 v95, v243
	v_mov_b32_e32 v96, v244
	v_mov_b32_e32 v97, v245
	v_mov_b32_e32 v106, v246
	v_mov_b32_e32 v107, v247
	v_mov_b32_e32 v108, v248
	v_mov_b32_e32 v109, v249
	v_mov_b32_e32 v110, v250
	v_mov_b32_e32 v111, v251
	v_mov_b32_e32 v112, v252
	v_mov_b32_e32 v113, v253
	v_mov_b32_e32 v114, v186
	v_mov_b32_e32 v115, v187
	v_mov_b32_e32 v116, v196
	v_mov_b32_e32 v117, v197
	v_mov_b32_e32 v101, v100
	v_mov_b32_e32 v103, v102
	s_and_b64 vcc, exec, s[18:19]
	s_nop 0
	v_lshlrev_b32_e32 v118, 16, v90
	v_and_b32_e32 v119, 0xffff0000, v90
	v_lshlrev_b32_e32 v90, 16, v91
	v_and_b32_e32 v91, 0xffff0000, v91
	v_pk_add_f32 v[90:91], v[90:91], v[100:101] neg_lo:[0,1] neg_hi:[0,1]
	v_pk_add_f32 v[118:119], v[118:119], v[100:101] neg_lo:[0,1] neg_hi:[0,1]
	v_pk_mul_f32 v[90:91], v[102:103], v[90:91]
	v_pk_mul_f32 v[118:119], v[102:103], v[118:119]
	s_nop 0
	v_pk_fma_f32 v[90:91], v[108:109], v[90:91], v[116:117]
	v_pk_fma_f32 v[106:107], v[106:107], v[118:119], v[114:115]
	v_pk_fma_f32 v[88:89], v[90:91], s[86:87], v[88:89] op_sel_hi:[1,0,1]
	v_lshlrev_b32_e32 v90, 16, v92
	v_and_b32_e32 v91, 0xffff0000, v92
	v_pk_add_f32 v[90:91], v[90:91], v[100:101] neg_lo:[0,1] neg_hi:[0,1]
	v_pk_fma_f32 v[86:87], v[106:107], s[86:87], v[86:87] op_sel_hi:[1,0,1]
	v_pk_mul_f32 v[90:91], v[102:103], v[90:91]
	s_nop 0
	v_pk_fma_f32 v[90:91], v[94:95], v[90:91], v[110:111]
	s_nop 0
	v_pk_fma_f32 v[82:83], v[90:91], s[86:87], v[82:83] op_sel_hi:[1,0,1]
	v_lshlrev_b32_e32 v90, 16, v93
	v_and_b32_e32 v91, 0xffff0000, v93
	v_pk_add_f32 v[90:91], v[90:91], v[100:101] neg_lo:[0,1] neg_hi:[0,1]
	s_nop 0
	v_pk_mul_f32 v[90:91], v[102:103], v[90:91]
	s_nop 0
	v_pk_fma_f32 v[90:91], v[96:97], v[90:91], v[112:113]
	s_nop 0
	v_pk_fma_f32 v[84:85], v[90:91], s[86:87], v[84:85] op_sel_hi:[1,0,1]
	s_cbranch_vccnz .LBB0_2036
	global_store_dwordx4 v[104:105], v[86:89], off offset:512
	global_store_dwordx4 v[104:105], v[82:85], off offset:528
	s_cbranch_execnz .LBB0_1999

; DI float bperm(float v, int srclane) { return __int_as_float(__builtin_amdgcn_ds_bpermute(srclane << 2, __float_as_int(v))); }
; DI u32x4 pack8(const float (&v)[8]) { u32x4 w; w.x = pk2(v[0], v[1]); w.y = pk2(v[2], v[3]); w.z = pk2(v[4], v[5]); w.w = pk2(v[6], v[7]); return w; }
; DI void row_stats(const float* STAT, int row, int fq, int lane, float& mu, float& rstd) {
;     const f32x4 a = *(const f32x4*)(STAT + (size_t)row * 32 + fq * 8), b = *(const f32x4*)(STAT + (size_t)row * 32 + fq * 8 + 4);
;     float s = (a[0] + a[2]) + (b[0] + b[2]), q = (a[1] + a[3]) + (b[1] + b[3]);
;     s += bperm(s, lane ^ 16); q += bperm(q, lane ^ 16); s += bperm(s, lane ^ 32); q += bperm(q, lane ^ 32);
;     mu = s * (1.0f / 1024.0f); rstd = __builtin_amdgcn_rsqf(fmaxf(q * (1.0f / 1024.0f) - mu * mu, 0.f) + EPS);
;     DI void operator()(const f32x4 (&acc)[2][2][4][2], const pg8::Unit& u, int wr, int wc, int fr, int fq) const {
;     ...
;             for (int m = 0; m < 4; ++m) { const int row = row0 + ai * 128 + m * 16; const size_t off = (size_t)row * DMODEL + col0; float mu, rstd; row_stats(STAT, row, fq, lane, mu, rstd);
; #pragma unroll
;                 for (int bj = 0; bj < 2; ++bj) { float p[8]; unpack8(*(const u32x4*)(XBin + off + bj * 128), p);
;                     const f32x4 g0 = *(const f32x4*)(g + col0 + bj * 128), g1 = *(const f32x4*)(g + col0 + bj * 128 + 4), b0 = *(const f32x4*)(b + col0 + bj * 128), b1 = *(const f32x4*)(b + col0 + bj * 128 + 4);
;                     float o[8];
; #pragma unroll
;                     for (int k = 0; k < 8; ++k) { const float gg = k < 4 ? g0[k & 3] : g1[k & 3], bb = k < 4 ? b0[k & 3] : b1[k & 3]; const float x1 = (p[k] - mu) * rstd * gg + bb; o[k] = x1 * ALPHA + acc[ai][bj][m][k >> 2][k & 3]; }
;                     if (out32) { *(f32x4*)(out32 + off + bj * 128) = (f32x4){o[0], o[1], o[2], o[3]}; *(f32x4*)(out32 + off + bj * 128 + 4) = (f32x4){o[4], o[5], o[6], o[7]}; }
;                     else *(u32x4*)(XBout + off + bj * 128) = pack8(o); }
.LBB0_1999:
	s_nop 0
	v_add_u32_e32 v82, 48, v146
	v_ashrrev_i32_e32 v83, 31, v82
	v_lshlrev_b64 v[84:85], 10, v[82:83]
	v_lshlrev_b64 v[82:83], 7, v[82:83]
	v_lshl_add_u64 v[82:83], s[36:37], 0, v[82:83]
	v_lshl_add_u64 v[86:87], v[144:145], 2, v[82:83]
	s_nop 1
	v_mov_b32_e32 v90, v220
	v_mov_b32_e32 v91, v221
	v_mov_b32_e32 v92, v222
	v_mov_b32_e32 v93, v223
	v_mov_b32_e32 v94, v224
	v_mov_b32_e32 v95, v225
	v_mov_b32_e32 v96, v226
	v_mov_b32_e32 v97, v227
	v_mov_b32_e32 v98, v228
	v_mov_b32_e32 v99, v229
	v_mov_b32_e32 v100, v230
	v_mov_b32_e32 v101, v231
	v_mov_b32_e32 v102, v232
	v_mov_b32_e32 v103, v233
	v_mov_b32_e32 v104, v234
	v_mov_b32_e32 v105, v235
	v_lshl_add_u64 v[88:89], v[84:85], 0, v[148:149]
	global_load_dwordx4 v[82:85], v[86:87], off offset:16
	global_load_dwordx4 v[106:109], v[86:87], off
	v_lshl_add_u64 v[178:179], v[88:89], 1, s[26:27]
	global_load_dwordx4 v[170:173], v[178:179], off
	global_load_dwordx4 v[174:177], v[178:179], off offset:256
	s_mov_b32 s2, 0x3a800000
	s_and_b64 vcc, exec, s[18:19]
	s_waitcnt vmcnt(3)
	v_pk_add_f32 v[82:83], v[82:83], v[84:85]
	s_waitcnt vmcnt(2)
	v_pk_add_f32 v[86:87], v[106:107], v[108:109]
	s_nop 0
	v_pk_add_f32 v[82:83], v[86:87], v[82:83]
	ds_bpermute_b32 v84, v163, v82
	ds_bpermute_b32 v85, v163, v83
	s_waitcnt lgkmcnt(0)
	v_pk_add_f32 v[82:83], v[82:83], v[84:85]
	ds_bpermute_b32 v84, v162, v82
	ds_bpermute_b32 v85, v162, v83
	s_waitcnt lgkmcnt(0)
	v_pk_add_f32 v[82:83], v[82:83], v[84:85]
	s_nop 0
	v_pk_mul_f32 v[84:85], v[82:83], s[2:3] op_sel_hi:[1,0]
	s_nop 0
	v_fma_f32 v82, -v84, v84, v85
	v_max_f32_e32 v82, 0, v82
	v_add_f32_e32 v82, 0x3727c5ac, v82
	v_rsq_f32_e32 v86, v82
	v_lshl_add_u64 v[82:83], v[88:89], 1, s[26:27]
	s_waitcnt vmcnt(0)
	v_mov_b32_e32 v106, v170
	v_mov_b32_e32 v107, v171
	v_mov_b32_e32 v108, v172
	v_mov_b32_e32 v109, v173
	v_lshl_add_u64 v[88:89], v[88:89], 2, s[28:29]
	s_waitcnt vmcnt(0)
	v_lshlrev_b32_e32 v110, 16, v106
	v_and_b32_e32 v111, 0xffff0000, v106
	v_pk_add_f32 v[110:111], v[110:111], v[84:85] op_sel_hi:[1,0] neg_lo:[0,1] neg_hi:[0,1]
	s_nop 0
	v_pk_mul_f32 v[110:111], v[110:111], v[86:87] op_sel_hi:[1,0]
	s_nop 0
	v_pk_fma_f32 v[94:95], v[94:95], v[110:111], v[102:103]
	s_nop 0
	v_pk_fma_f32 v[78:79], v[94:95], s[86:87], v[78:79] op_sel_hi:[1,0,1]
	v_lshlrev_b32_e32 v94, 16, v107
	v_and_b32_e32 v95, 0xffff0000, v107
	v_pk_add_f32 v[94:95], v[94:95], v[84:85] op_sel_hi:[1,0] neg_lo:[0,1] neg_hi:[0,1]
	s_nop 0
	v_pk_mul_f32 v[94:95], v[94:95], v[86:87] op_sel_hi:[1,0]
	s_nop 0
	v_pk_fma_f32 v[94:95], v[96:97], v[94:95], v[104:105]
	s_nop 0
	v_pk_fma_f32 v[80:81], v[94:95], s[86:87], v[80:81] op_sel_hi:[1,0,1]
	v_lshlrev_b32_e32 v94, 16, v108
	v_and_b32_e32 v95, 0xffff0000, v108
	v_pk_add_f32 v[94:95], v[94:95], v[84:85] op_sel_hi:[1,0] neg_lo:[0,1] neg_hi:[0,1]
	s_nop 0
	v_pk_mul_f32 v[94:95], v[94:95], v[86:87] op_sel_hi:[1,0]
	s_nop 0
	v_pk_fma_f32 v[90:91], v[90:91], v[94:95], v[98:99]
	s_nop 0
	v_pk_fma_f32 v[74:75], v[90:91], s[86:87], v[74:75] op_sel_hi:[1,0,1]
	v_lshlrev_b32_e32 v90, 16, v109
	v_and_b32_e32 v91, 0xffff0000, v109
	v_pk_add_f32 v[90:91], v[90:91], v[84:85] op_sel_hi:[1,0] neg_lo:[0,1] neg_hi:[0,1]
	s_nop 0
	v_pk_mul_f32 v[90:91], v[90:91], v[86:87] op_sel_hi:[1,0]
	s_nop 0
	v_pk_fma_f32 v[90:91], v[92:93], v[90:91], v[100:101]
	s_nop 0
	v_pk_fma_f32 v[76:77], v[90:91], s[86:87], v[76:77] op_sel_hi:[1,0,1]
	s_cbranch_vccnz .LBB0_2037
	global_store_dwordx4 v[88:89], v[78:81], off
	global_store_dwordx4 v[88:89], v[74:77], off offset:16
	s_cbranch_execnz .LBB0_2002

; DI u32x4 pack8(const float (&v)[8]) { u32x4 w; w.x = pk2(v[0], v[1]); w.y = pk2(v[2], v[3]); w.z = pk2(v[4], v[5]); w.w = pk2(v[6], v[7]); return w; }
;     DI void operator()(const f32x4 (&acc)[2][2][4][2], const pg8::Unit& u, int wr, int wc, int fr, int fq) const {
;     ...
;                 for (int bj = 0; bj < 2; ++bj) { float p[8]; unpack8(*(const u32x4*)(XBin + off + bj * 128), p);
;                     const f32x4 g0 = *(const f32x4*)(g + col0 + bj * 128), g1 = *(const f32x4*)(g + col0 + bj * 128 + 4), b0 = *(const f32x4*)(b + col0 + bj * 128), b1 = *(const f32x4*)(b + col0 + bj * 128 + 4);
;                     float o[8];
; #pragma unroll
;                     for (int k = 0; k < 8; ++k) { const float gg = k < 4 ? g0[k & 3] : g1[k & 3], bb = k < 4 ? b0[k & 3] : b1[k & 3]; const float x1 = (p[k] - mu) * rstd * gg + bb; o[k] = x1 * ALPHA + acc[ai][bj][m][k >> 2][k & 3]; }
;                     if (out32) { *(f32x4*)(out32 + off + bj * 128) = (f32x4){o[0], o[1], o[2], o[3]}; *(f32x4*)(out32 + off + bj * 128 + 4) = (f32x4){o[4], o[5], o[6], o[7]}; }
;                     else *(u32x4*)(XBout + off + bj * 128) = pack8(o); }
.LBB0_2002:
	s_nop 1
	v_mov_b32_e32 v74, v174
	v_mov_b32_e32 v75, v175
	v_mov_b32_e32 v76, v176
	v_mov_b32_e32 v77, v177
	s_nop 0
	s_nop 1
	v_mov_b32_e32 v78, v242
	v_mov_b32_e32 v79, v243
	v_mov_b32_e32 v80, v244
	v_mov_b32_e32 v81, v245
	v_mov_b32_e32 v90, v246
	v_mov_b32_e32 v91, v247
	v_mov_b32_e32 v92, v248
	v_mov_b32_e32 v93, v249
	v_mov_b32_e32 v94, v250
	v_mov_b32_e32 v95, v251
	v_mov_b32_e32 v96, v252
	v_mov_b32_e32 v97, v253
	v_mov_b32_e32 v98, v186
	v_mov_b32_e32 v99, v187
	v_mov_b32_e32 v100, v196
	v_mov_b32_e32 v101, v197
	v_mov_b32_e32 v85, v84
	v_mov_b32_e32 v87, v86
	s_and_b64 vcc, exec, s[18:19]
	s_nop 0
	v_lshlrev_b32_e32 v102, 16, v74
	v_and_b32_e32 v103, 0xffff0000, v74
	v_lshlrev_b32_e32 v74, 16, v75
	v_and_b32_e32 v75, 0xffff0000, v75
	v_pk_add_f32 v[74:75], v[74:75], v[84:85] neg_lo:[0,1] neg_hi:[0,1]
	v_pk_add_f32 v[102:103], v[102:103], v[84:85] neg_lo:[0,1] neg_hi:[0,1]
	v_pk_mul_f32 v[74:75], v[86:87], v[74:75]
	v_pk_mul_f32 v[102:103], v[86:87], v[102:103]
	s_nop 0
	v_pk_fma_f32 v[74:75], v[92:93], v[74:75], v[100:101]
	v_pk_fma_f32 v[90:91], v[90:91], v[102:103], v[98:99]
	v_pk_fma_f32 v[72:73], v[74:75], s[86:87], v[72:73] op_sel_hi:[1,0,1]
	v_lshlrev_b32_e32 v74, 16, v76
	v_and_b32_e32 v75, 0xffff0000, v76
	v_pk_add_f32 v[74:75], v[74:75], v[84:85] neg_lo:[0,1] neg_hi:[0,1]
	v_pk_fma_f32 v[70:71], v[90:91], s[86:87], v[70:71] op_sel_hi:[1,0,1]
	v_pk_mul_f32 v[74:75], v[86:87], v[74:75]
	s_nop 0
	v_pk_fma_f32 v[74:75], v[78:79], v[74:75], v[94:95]
	s_nop 0
	v_pk_fma_f32 v[66:67], v[74:75], s[86:87], v[66:67] op_sel_hi:[1,0,1]
	v_lshlrev_b32_e32 v74, 16, v77
	v_and_b32_e32 v75, 0xffff0000, v77
	v_pk_add_f32 v[74:75], v[74:75], v[84:85] neg_lo:[0,1] neg_hi:[0,1]
	s_nop 0
	v_pk_mul_f32 v[74:75], v[86:87], v[74:75]
	s_nop 0
	v_pk_fma_f32 v[74:75], v[80:81], v[74:75], v[96:97]
	s_nop 0
	v_pk_fma_f32 v[68:69], v[74:75], s[86:87], v[68:69] op_sel_hi:[1,0,1]
	s_cbranch_vccnz .LBB0_2038
	global_store_dwordx4 v[88:89], v[70:73], off offset:512
	global_store_dwordx4 v[88:89], v[66:69], off offset:528
	s_cbranch_execnz .LBB0_2005

; DI float bperm(float v, int srclane) { return __int_as_float(__builtin_amdgcn_ds_bpermute(srclane << 2, __float_as_int(v))); }
; DI u32x4 pack8(const float (&v)[8]) { u32x4 w; w.x = pk2(v[0], v[1]); w.y = pk2(v[2], v[3]); w.z = pk2(v[4], v[5]); w.w = pk2(v[6], v[7]); return w; }
; DI void row_stats(const float* STAT, int row, int fq, int lane, float& mu, float& rstd) {
;     const f32x4 a = *(const f32x4*)(STAT + (size_t)row * 32 + fq * 8), b = *(const f32x4*)(STAT + (size_t)row * 32 + fq * 8 + 4);
;     float s = (a[0] + a[2]) + (b[0] + b[2]), q = (a[1] + a[3]) + (b[1] + b[3]);
;     s += bperm(s, lane ^ 16); q += bperm(q, lane ^ 16); s += bperm(s, lane ^ 32); q += bperm(q, lane ^ 32);
;     mu = s * (1.0f / 1024.0f); rstd = __builtin_amdgcn_rsqf(fmaxf(q * (1.0f / 1024.0f) - mu * mu, 0.f) + EPS);
;     DI void operator()(const f32x4 (&acc)[2][2][4][2], const pg8::Unit& u, int wr, int wc, int fr, int fq) const {
;     ...
;             for (int m = 0; m < 4; ++m) { const int row = row0 + ai * 128 + m * 16; const size_t off = (size_t)row * DMODEL + col0; float mu, rstd; row_stats(STAT, row, fq, lane, mu, rstd);
; #pragma unroll
;                 for (int bj = 0; bj < 2; ++bj) { float p[8]; unpack8(*(const u32x4*)(XBin + off + bj * 128), p);
;                     const f32x4 g0 = *(const f32x4*)(g + col0 + bj * 128), g1 = *(const f32x4*)(g + col0 + bj * 128 + 4), b0 = *(const f32x4*)(b + col0 + bj * 128), b1 = *(const f32x4*)(b + col0 + bj * 128 + 4);
;                     float o[8];
; #pragma unroll
;                     for (int k = 0; k < 8; ++k) { const float gg = k < 4 ? g0[k & 3] : g1[k & 3], bb = k < 4 ? b0[k & 3] : b1[k & 3]; const float x1 = (p[k] - mu) * rstd * gg + bb; o[k] = x1 * ALPHA + acc[ai][bj][m][k >> 2][k & 3]; }
;                     if (out32) { *(f32x4*)(out32 + off + bj * 128) = (f32x4){o[0], o[1], o[2], o[3]}; *(f32x4*)(out32 + off + bj * 128 + 4) = (f32x4){o[4], o[5], o[6], o[7]}; }
;                     else *(u32x4*)(XBout + off + bj * 128) = pack8(o); }
.LBB0_2005:
	s_nop 0
	v_add_u32_e32 v66, 0x80, v146
	v_ashrrev_i32_e32 v67, 31, v66
	v_lshlrev_b64 v[68:69], 10, v[66:67]
	v_lshlrev_b64 v[66:67], 7, v[66:67]
	v_lshl_add_u64 v[66:67], s[36:37], 0, v[66:67]
	v_lshl_add_u64 v[70:71], v[144:145], 2, v[66:67]
	v_lshl_add_u64 v[72:73], v[68:69], 0, v[148:149]
	global_load_dwordx4 v[66:69], v[70:71], off offset:16
	global_load_dwordx4 v[74:77], v[70:71], off
	v_lshl_add_u64 v[178:179], v[72:73], 1, s[26:27]
	global_load_dwordx4 v[170:173], v[178:179], off
	global_load_dwordx4 v[174:177], v[178:179], off offset:256
	s_mov_b32 s2, 0x3a800000
	s_and_b64 vcc, exec, s[18:19]
	s_waitcnt vmcnt(3)
	v_pk_add_f32 v[66:67], v[66:67], v[68:69]
	s_waitcnt vmcnt(2)
	v_pk_add_f32 v[70:71], v[74:75], v[76:77]
	s_nop 0
	v_pk_add_f32 v[66:67], v[70:71], v[66:67]
	ds_bpermute_b32 v68, v163, v66
	ds_bpermute_b32 v69, v163, v67
	s_waitcnt lgkmcnt(0)
	v_pk_add_f32 v[66:67], v[66:67], v[68:69]
	ds_bpermute_b32 v68, v162, v66
	ds_bpermute_b32 v69, v162, v67
	s_waitcnt lgkmcnt(0)
	v_pk_add_f32 v[66:67], v[66:67], v[68:69]
	s_nop 0
	v_pk_mul_f32 v[68:69], v[66:67], s[2:3] op_sel_hi:[1,0]
	s_nop 0
	v_fma_f32 v66, -v68, v68, v69
	v_max_f32_e32 v66, 0, v66
	v_add_f32_e32 v66, 0x3727c5ac, v66
	v_rsq_f32_e32 v70, v66
	v_lshl_add_u64 v[66:67], v[72:73], 1, s[26:27]
	s_waitcnt vmcnt(0)
	v_mov_b32_e32 v74, v170
	v_mov_b32_e32 v75, v171
	v_mov_b32_e32 v76, v172
	v_mov_b32_e32 v77, v173
	s_nop 1
	v_mov_b32_e32 v78, v220
	v_mov_b32_e32 v79, v221
	v_mov_b32_e32 v80, v222
	v_mov_b32_e32 v81, v223
	v_mov_b32_e32 v82, v224
	v_mov_b32_e32 v83, v225
	v_mov_b32_e32 v84, v226
	v_mov_b32_e32 v85, v227
	v_mov_b32_e32 v86, v228
	v_mov_b32_e32 v87, v229
	v_mov_b32_e32 v88, v230
	v_mov_b32_e32 v89, v231
	v_mov_b32_e32 v90, v232
	v_mov_b32_e32 v91, v233
	v_mov_b32_e32 v92, v234
	v_mov_b32_e32 v93, v235
	v_lshl_add_u64 v[72:73], v[72:73], 2, s[28:29]
	s_waitcnt vmcnt(0)
	v_lshlrev_b32_e32 v94, 16, v74
	v_and_b32_e32 v95, 0xffff0000, v74
	v_lshlrev_b32_e32 v74, 16, v75
	v_and_b32_e32 v75, 0xffff0000, v75
	v_pk_add_f32 v[74:75], v[74:75], v[68:69] op_sel_hi:[1,0] neg_lo:[0,1] neg_hi:[0,1]
	v_pk_add_f32 v[94:95], v[94:95], v[68:69] op_sel_hi:[1,0] neg_lo:[0,1] neg_hi:[0,1]
	v_pk_mul_f32 v[74:75], v[74:75], v[70:71] op_sel_hi:[1,0]
	v_pk_mul_f32 v[94:95], v[94:95], v[70:71] op_sel_hi:[1,0]
	s_waitcnt vmcnt(0)
	v_pk_fma_f32 v[74:75], v[84:85], v[74:75], v[92:93]
	v_pk_fma_f32 v[82:83], v[82:83], v[94:95], v[90:91]
	v_pk_fma_f32 v[64:65], v[74:75], s[86:87], v[64:65] op_sel_hi:[1,0,1]
	v_lshlrev_b32_e32 v74, 16, v76
	v_and_b32_e32 v75, 0xffff0000, v76
	v_pk_add_f32 v[74:75], v[74:75], v[68:69] op_sel_hi:[1,0] neg_lo:[0,1] neg_hi:[0,1]
	v_pk_fma_f32 v[62:63], v[82:83], s[86:87], v[62:63] op_sel_hi:[1,0,1]
	v_pk_mul_f32 v[74:75], v[74:75], v[70:71] op_sel_hi:[1,0]
	s_nop 0
	v_pk_fma_f32 v[74:75], v[78:79], v[74:75], v[86:87]
	s_nop 0
	v_pk_fma_f32 v[58:59], v[74:75], s[86:87], v[58:59] op_sel_hi:[1,0,1]
	v_lshlrev_b32_e32 v74, 16, v77
	v_and_b32_e32 v75, 0xffff0000, v77
	v_pk_add_f32 v[74:75], v[74:75], v[68:69] op_sel_hi:[1,0] neg_lo:[0,1] neg_hi:[0,1]
	s_nop 0
	v_pk_mul_f32 v[74:75], v[74:75], v[70:71] op_sel_hi:[1,0]
	s_nop 0
	v_pk_fma_f32 v[74:75], v[80:81], v[74:75], v[88:89]
	s_nop 0
	v_pk_fma_f32 v[60:61], v[74:75], s[86:87], v[60:61] op_sel_hi:[1,0,1]
	s_cbranch_vccnz .LBB0_2039
	global_store_dwordx4 v[72:73], v[62:65], off
	global_store_dwordx4 v[72:73], v[58:61], off offset:16
	s_cbranch_execnz .LBB0_2008

; DI u32x4 pack8(const float (&v)[8]) { u32x4 w; w.x = pk2(v[0], v[1]); w.y = pk2(v[2], v[3]); w.z = pk2(v[4], v[5]); w.w = pk2(v[6], v[7]); return w; }
;     DI void operator()(const f32x4 (&acc)[2][2][4][2], const pg8::Unit& u, int wr, int wc, int fr, int fq) const {
;     ...
;                 for (int bj = 0; bj < 2; ++bj) { float p[8]; unpack8(*(const u32x4*)(XBin + off + bj * 128), p);
;                     const f32x4 g0 = *(const f32x4*)(g + col0 + bj * 128), g1 = *(const f32x4*)(g + col0 + bj * 128 + 4), b0 = *(const f32x4*)(b + col0 + bj * 128), b1 = *(const f32x4*)(b + col0 + bj * 128 + 4);
;                     float o[8];
; #pragma unroll
;                     for (int k = 0; k < 8; ++k) { const float gg = k < 4 ? g0[k & 3] : g1[k & 3], bb = k < 4 ? b0[k & 3] : b1[k & 3]; const float x1 = (p[k] - mu) * rstd * gg + bb; o[k] = x1 * ALPHA + acc[ai][bj][m][k >> 2][k & 3]; }
;                     if (out32) { *(f32x4*)(out32 + off + bj * 128) = (f32x4){o[0], o[1], o[2], o[3]}; *(f32x4*)(out32 + off + bj * 128 + 4) = (f32x4){o[4], o[5], o[6], o[7]}; }
;                     else *(u32x4*)(XBout + off + bj * 128) = pack8(o); }
.LBB0_2008:
	s_nop 1
	v_mov_b32_e32 v58, v174
	v_mov_b32_e32 v59, v175
	v_mov_b32_e32 v60, v176
	v_mov_b32_e32 v61, v177
	s_nop 0
	s_nop 1
	v_mov_b32_e32 v62, v242
	v_mov_b32_e32 v63, v243
	v_mov_b32_e32 v64, v244
	v_mov_b32_e32 v65, v245
	v_mov_b32_e32 v74, v246
	v_mov_b32_e32 v75, v247
	v_mov_b32_e32 v76, v248
	v_mov_b32_e32 v77, v249
	v_mov_b32_e32 v78, v250
	v_mov_b32_e32 v79, v251
	v_mov_b32_e32 v80, v252
	v_mov_b32_e32 v81, v253
	v_mov_b32_e32 v82, v186
	v_mov_b32_e32 v83, v187
	v_mov_b32_e32 v84, v196
	v_mov_b32_e32 v85, v197
	v_mov_b32_e32 v69, v68
	v_mov_b32_e32 v71, v70
	s_and_b64 vcc, exec, s[18:19]
	s_nop 0
	v_lshlrev_b32_e32 v86, 16, v58
	v_and_b32_e32 v87, 0xffff0000, v58
	v_lshlrev_b32_e32 v58, 16, v59
	v_and_b32_e32 v59, 0xffff0000, v59
	v_pk_add_f32 v[58:59], v[58:59], v[68:69] neg_lo:[0,1] neg_hi:[0,1]
	v_pk_add_f32 v[86:87], v[86:87], v[68:69] neg_lo:[0,1] neg_hi:[0,1]
	v_pk_mul_f32 v[58:59], v[70:71], v[58:59]
	v_pk_mul_f32 v[86:87], v[70:71], v[86:87]
	s_nop 0
	v_pk_fma_f32 v[58:59], v[76:77], v[58:59], v[84:85]
	v_pk_fma_f32 v[74:75], v[74:75], v[86:87], v[82:83]
	v_pk_fma_f32 v[56:57], v[58:59], s[86:87], v[56:57] op_sel_hi:[1,0,1]
	v_lshlrev_b32_e32 v58, 16, v60
	v_and_b32_e32 v59, 0xffff0000, v60
	v_pk_add_f32 v[58:59], v[58:59], v[68:69] neg_lo:[0,1] neg_hi:[0,1]
	v_pk_fma_f32 v[54:55], v[74:75], s[86:87], v[54:55] op_sel_hi:[1,0,1]
	v_pk_mul_f32 v[58:59], v[70:71], v[58:59]
	s_nop 0
	v_pk_fma_f32 v[58:59], v[62:63], v[58:59], v[78:79]
	s_nop 0
	v_pk_fma_f32 v[50:51], v[58:59], s[86:87], v[50:51] op_sel_hi:[1,0,1]
	v_lshlrev_b32_e32 v58, 16, v61
	v_and_b32_e32 v59, 0xffff0000, v61
	v_pk_add_f32 v[58:59], v[58:59], v[68:69] neg_lo:[0,1] neg_hi:[0,1]
	s_nop 0
	v_pk_mul_f32 v[58:59], v[70:71], v[58:59]
	s_nop 0
	v_pk_fma_f32 v[58:59], v[64:65], v[58:59], v[80:81]
	s_nop 0
	v_pk_fma_f32 v[52:53], v[58:59], s[86:87], v[52:53] op_sel_hi:[1,0,1]
	s_cbranch_vccnz .LBB0_2040
	global_store_dwordx4 v[72:73], v[54:57], off offset:512
	global_store_dwordx4 v[72:73], v[50:53], off offset:528
	s_cbranch_execnz .LBB0_2011

; DI float bperm(float v, int srclane) { return __int_as_float(__builtin_amdgcn_ds_bpermute(srclane << 2, __float_as_int(v))); }
; DI u32x4 pack8(const float (&v)[8]) { u32x4 w; w.x = pk2(v[0], v[1]); w.y = pk2(v[2], v[3]); w.z = pk2(v[4], v[5]); w.w = pk2(v[6], v[7]); return w; }
; DI void row_stats(const float* STAT, int row, int fq, int lane, float& mu, float& rstd) {
;     const f32x4 a = *(const f32x4*)(STAT + (size_t)row * 32 + fq * 8), b = *(const f32x4*)(STAT + (size_t)row * 32 + fq * 8 + 4);
;     float s = (a[0] + a[2]) + (b[0] + b[2]), q = (a[1] + a[3]) + (b[1] + b[3]);
;     s += bperm(s, lane ^ 16); q += bperm(q, lane ^ 16); s += bperm(s, lane ^ 32); q += bperm(q, lane ^ 32);
;     mu = s * (1.0f / 1024.0f); rstd = __builtin_amdgcn_rsqf(fmaxf(q * (1.0f / 1024.0f) - mu * mu, 0.f) + EPS);
;     DI void operator()(const f32x4 (&acc)[2][2][4][2], const pg8::Unit& u, int wr, int wc, int fr, int fq) const {
;     ...
;             for (int m = 0; m < 4; ++m) { const int row = row0 + ai * 128 + m * 16; const size_t off = (size_t)row * DMODEL + col0; float mu, rstd; row_stats(STAT, row, fq, lane, mu, rstd);
; #pragma unroll
;                 for (int bj = 0; bj < 2; ++bj) { float p[8]; unpack8(*(const u32x4*)(XBin + off + bj * 128), p);
;                     const f32x4 g0 = *(const f32x4*)(g + col0 + bj * 128), g1 = *(const f32x4*)(g + col0 + bj * 128 + 4), b0 = *(const f32x4*)(b + col0 + bj * 128), b1 = *(const f32x4*)(b + col0 + bj * 128 + 4);
;                     float o[8];
; #pragma unroll
;                     for (int k = 0; k < 8; ++k) { const float gg = k < 4 ? g0[k & 3] : g1[k & 3], bb = k < 4 ? b0[k & 3] : b1[k & 3]; const float x1 = (p[k] - mu) * rstd * gg + bb; o[k] = x1 * ALPHA + acc[ai][bj][m][k >> 2][k & 3]; }
;                     if (out32) { *(f32x4*)(out32 + off + bj * 128) = (f32x4){o[0], o[1], o[2], o[3]}; *(f32x4*)(out32 + off + bj * 128 + 4) = (f32x4){o[4], o[5], o[6], o[7]}; }
;                     else *(u32x4*)(XBout + off + bj * 128) = pack8(o); }
.LBB0_2011:
	s_nop 0
	v_add_u32_e32 v50, 0x90, v146
	v_ashrrev_i32_e32 v51, 31, v50
	v_lshlrev_b64 v[52:53], 10, v[50:51]
	v_lshlrev_b64 v[50:51], 7, v[50:51]
	v_lshl_add_u64 v[50:51], s[36:37], 0, v[50:51]
	v_lshl_add_u64 v[54:55], v[144:145], 2, v[50:51]
	s_nop 1
	v_mov_b32_e32 v58, v220
	v_mov_b32_e32 v59, v221
	v_mov_b32_e32 v60, v222
	v_mov_b32_e32 v61, v223
	v_mov_b32_e32 v62, v224
	v_mov_b32_e32 v63, v225
	v_mov_b32_e32 v64, v226
	v_mov_b32_e32 v65, v227
	v_mov_b32_e32 v66, v228
	v_mov_b32_e32 v67, v229
	v_mov_b32_e32 v68, v230
	v_mov_b32_e32 v69, v231
	v_mov_b32_e32 v70, v232
	v_mov_b32_e32 v71, v233
	v_mov_b32_e32 v72, v234
	v_mov_b32_e32 v73, v235
	v_lshl_add_u64 v[56:57], v[52:53], 0, v[148:149]
	global_load_dwordx4 v[50:53], v[54:55], off offset:16
	global_load_dwordx4 v[74:77], v[54:55], off
	v_lshl_add_u64 v[178:179], v[56:57], 1, s[26:27]
	global_load_dwordx4 v[170:173], v[178:179], off
	global_load_dwordx4 v[174:177], v[178:179], off offset:256
	s_mov_b32 s2, 0x3a800000
	s_and_b64 vcc, exec, s[18:19]
	s_waitcnt vmcnt(3)
	v_pk_add_f32 v[50:51], v[50:51], v[52:53]
	s_waitcnt vmcnt(2)
	v_pk_add_f32 v[54:55], v[74:75], v[76:77]
	s_nop 0
	v_pk_add_f32 v[50:51], v[54:55], v[50:51]
	ds_bpermute_b32 v52, v163, v50
	ds_bpermute_b32 v53, v163, v51
	s_waitcnt lgkmcnt(0)
	v_pk_add_f32 v[50:51], v[50:51], v[52:53]
	ds_bpermute_b32 v52, v162, v50
	ds_bpermute_b32 v53, v162, v51
	s_waitcnt lgkmcnt(0)
	v_pk_add_f32 v[50:51], v[50:51], v[52:53]
	s_nop 0
	v_pk_mul_f32 v[52:53], v[50:51], s[2:3] op_sel_hi:[1,0]
	s_nop 0
	v_fma_f32 v50, -v52, v52, v53
	v_max_f32_e32 v50, 0, v50
	v_add_f32_e32 v50, 0x3727c5ac, v50
	v_rsq_f32_e32 v54, v50
	v_lshl_add_u64 v[50:51], v[56:57], 1, s[26:27]
	s_waitcnt vmcnt(0)
	v_mov_b32_e32 v74, v170
	v_mov_b32_e32 v75, v171
	v_mov_b32_e32 v76, v172
	v_mov_b32_e32 v77, v173
	v_lshl_add_u64 v[56:57], v[56:57], 2, s[28:29]
	s_waitcnt vmcnt(0)
	v_lshlrev_b32_e32 v78, 16, v74
	v_and_b32_e32 v79, 0xffff0000, v74
	v_pk_add_f32 v[78:79], v[78:79], v[52:53] op_sel_hi:[1,0] neg_lo:[0,1] neg_hi:[0,1]
	s_nop 0
	v_pk_mul_f32 v[78:79], v[78:79], v[54:55] op_sel_hi:[1,0]
	s_nop 0
	v_pk_fma_f32 v[62:63], v[62:63], v[78:79], v[70:71]
	s_nop 0
	v_pk_fma_f32 v[46:47], v[62:63], s[86:87], v[46:47] op_sel_hi:[1,0,1]
	v_lshlrev_b32_e32 v62, 16, v75
	v_and_b32_e32 v63, 0xffff0000, v75
	v_pk_add_f32 v[62:63], v[62:63], v[52:53] op_sel_hi:[1,0] neg_lo:[0,1] neg_hi:[0,1]
	s_nop 0
	v_pk_mul_f32 v[62:63], v[62:63], v[54:55] op_sel_hi:[1,0]
	s_nop 0
	v_pk_fma_f32 v[62:63], v[64:65], v[62:63], v[72:73]
	s_nop 0
	v_pk_fma_f32 v[48:49], v[62:63], s[86:87], v[48:49] op_sel_hi:[1,0,1]
	v_lshlrev_b32_e32 v62, 16, v76
	v_and_b32_e32 v63, 0xffff0000, v76
	v_pk_add_f32 v[62:63], v[62:63], v[52:53] op_sel_hi:[1,0] neg_lo:[0,1] neg_hi:[0,1]
	s_nop 0
	v_pk_mul_f32 v[62:63], v[62:63], v[54:55] op_sel_hi:[1,0]
	s_nop 0
	v_pk_fma_f32 v[58:59], v[58:59], v[62:63], v[66:67]
	s_nop 0
	v_pk_fma_f32 v[42:43], v[58:59], s[86:87], v[42:43] op_sel_hi:[1,0,1]
	v_lshlrev_b32_e32 v58, 16, v77
	v_and_b32_e32 v59, 0xffff0000, v77
	v_pk_add_f32 v[58:59], v[58:59], v[52:53] op_sel_hi:[1,0] neg_lo:[0,1] neg_hi:[0,1]
	s_nop 0
	v_pk_mul_f32 v[58:59], v[58:59], v[54:55] op_sel_hi:[1,0]
	s_nop 0
	v_pk_fma_f32 v[58:59], v[60:61], v[58:59], v[68:69]
	s_nop 0
	v_pk_fma_f32 v[44:45], v[58:59], s[86:87], v[44:45] op_sel_hi:[1,0,1]
	s_cbranch_vccnz .LBB0_2041
	global_store_dwordx4 v[56:57], v[46:49], off
	global_store_dwordx4 v[56:57], v[42:45], off offset:16
	s_cbranch_execnz .LBB0_2014

; DI u32x4 pack8(const float (&v)[8]) { u32x4 w; w.x = pk2(v[0], v[1]); w.y = pk2(v[2], v[3]); w.z = pk2(v[4], v[5]); w.w = pk2(v[6], v[7]); return w; }
;     DI void operator()(const f32x4 (&acc)[2][2][4][2], const pg8::Unit& u, int wr, int wc, int fr, int fq) const {
;     ...
;                 for (int bj = 0; bj < 2; ++bj) { float p[8]; unpack8(*(const u32x4*)(XBin + off + bj * 128), p);
;                     const f32x4 g0 = *(const f32x4*)(g + col0 + bj * 128), g1 = *(const f32x4*)(g + col0 + bj * 128 + 4), b0 = *(const f32x4*)(b + col0 + bj * 128), b1 = *(const f32x4*)(b + col0 + bj * 128 + 4);
;                     float o[8];
; #pragma unroll
;                     for (int k = 0; k < 8; ++k) { const float gg = k < 4 ? g0[k & 3] : g1[k & 3], bb = k < 4 ? b0[k & 3] : b1[k & 3]; const float x1 = (p[k] - mu) * rstd * gg + bb; o[k] = x1 * ALPHA + acc[ai][bj][m][k >> 2][k & 3]; }
;                     if (out32) { *(f32x4*)(out32 + off + bj * 128) = (f32x4){o[0], o[1], o[2], o[3]}; *(f32x4*)(out32 + off + bj * 128 + 4) = (f32x4){o[4], o[5], o[6], o[7]}; }
;                     else *(u32x4*)(XBout + off + bj * 128) = pack8(o); }
.LBB0_2014:
	s_nop 1
	v_mov_b32_e32 v42, v174
	v_mov_b32_e32 v43, v175
	v_mov_b32_e32 v44, v176
	v_mov_b32_e32 v45, v177
	s_nop 0
	s_nop 1
	v_mov_b32_e32 v46, v242
	v_mov_b32_e32 v47, v243
	v_mov_b32_e32 v48, v244
	v_mov_b32_e32 v49, v245
	v_mov_b32_e32 v58, v246
	v_mov_b32_e32 v59, v247
	v_mov_b32_e32 v60, v248
	v_mov_b32_e32 v61, v249
	v_mov_b32_e32 v62, v250
	v_mov_b32_e32 v63, v251
	v_mov_b32_e32 v64, v252
	v_mov_b32_e32 v65, v253
	v_mov_b32_e32 v66, v186
	v_mov_b32_e32 v67, v187
	v_mov_b32_e32 v68, v196
	v_mov_b32_e32 v69, v197
	v_mov_b32_e32 v53, v52
	v_mov_b32_e32 v55, v54
	s_and_b64 vcc, exec, s[18:19]
	s_nop 0
	v_lshlrev_b32_e32 v70, 16, v42
	v_and_b32_e32 v71, 0xffff0000, v42
	v_lshlrev_b32_e32 v42, 16, v43
	v_and_b32_e32 v43, 0xffff0000, v43
	v_pk_add_f32 v[42:43], v[42:43], v[52:53] neg_lo:[0,1] neg_hi:[0,1]
	v_pk_add_f32 v[70:71], v[70:71], v[52:53] neg_lo:[0,1] neg_hi:[0,1]
	v_pk_mul_f32 v[42:43], v[54:55], v[42:43]
	v_pk_mul_f32 v[70:71], v[54:55], v[70:71]
	s_nop 0
	v_pk_fma_f32 v[42:43], v[60:61], v[42:43], v[68:69]
	v_pk_fma_f32 v[58:59], v[58:59], v[70:71], v[66:67]
	v_pk_fma_f32 v[40:41], v[42:43], s[86:87], v[40:41] op_sel_hi:[1,0,1]
	v_lshlrev_b32_e32 v42, 16, v44
	v_and_b32_e32 v43, 0xffff0000, v44
	v_pk_add_f32 v[42:43], v[42:43], v[52:53] neg_lo:[0,1] neg_hi:[0,1]
	v_pk_fma_f32 v[38:39], v[58:59], s[86:87], v[38:39] op_sel_hi:[1,0,1]
	v_pk_mul_f32 v[42:43], v[54:55], v[42:43]
	s_nop 0
	v_pk_fma_f32 v[42:43], v[46:47], v[42:43], v[62:63]
	s_nop 0
	v_pk_fma_f32 v[34:35], v[42:43], s[86:87], v[34:35] op_sel_hi:[1,0,1]
	v_lshlrev_b32_e32 v42, 16, v45
	v_and_b32_e32 v43, 0xffff0000, v45
	v_pk_add_f32 v[42:43], v[42:43], v[52:53] neg_lo:[0,1] neg_hi:[0,1]
	s_nop 0
	v_pk_mul_f32 v[42:43], v[54:55], v[42:43]
	s_nop 0
	v_pk_fma_f32 v[42:43], v[48:49], v[42:43], v[64:65]
	s_nop 0
	v_pk_fma_f32 v[36:37], v[42:43], s[86:87], v[36:37] op_sel_hi:[1,0,1]
	s_cbranch_vccnz .LBB0_2042
	global_store_dwordx4 v[56:57], v[38:41], off offset:512
	global_store_dwordx4 v[56:57], v[34:37], off offset:528
	s_cbranch_execnz .LBB0_2017

; DI float bperm(float v, int srclane) { return __int_as_float(__builtin_amdgcn_ds_bpermute(srclane << 2, __float_as_int(v))); }
; DI u32x4 pack8(const float (&v)[8]) { u32x4 w; w.x = pk2(v[0], v[1]); w.y = pk2(v[2], v[3]); w.z = pk2(v[4], v[5]); w.w = pk2(v[6], v[7]); return w; }
; DI void row_stats(const float* STAT, int row, int fq, int lane, float& mu, float& rstd) {
;     const f32x4 a = *(const f32x4*)(STAT + (size_t)row * 32 + fq * 8), b = *(const f32x4*)(STAT + (size_t)row * 32 + fq * 8 + 4);
;     float s = (a[0] + a[2]) + (b[0] + b[2]), q = (a[1] + a[3]) + (b[1] + b[3]);
;     s += bperm(s, lane ^ 16); q += bperm(q, lane ^ 16); s += bperm(s, lane ^ 32); q += bperm(q, lane ^ 32);
;     mu = s * (1.0f / 1024.0f); rstd = __builtin_amdgcn_rsqf(fmaxf(q * (1.0f / 1024.0f) - mu * mu, 0.f) + EPS);
;     DI void operator()(const f32x4 (&acc)[2][2][4][2], const pg8::Unit& u, int wr, int wc, int fr, int fq) const {
;     ...
;             for (int m = 0; m < 4; ++m) { const int row = row0 + ai * 128 + m * 16; const size_t off = (size_t)row * DMODEL + col0; float mu, rstd; row_stats(STAT, row, fq, lane, mu, rstd);
; #pragma unroll
;                 for (int bj = 0; bj < 2; ++bj) { float p[8]; unpack8(*(const u32x4*)(XBin + off + bj * 128), p);
;                     const f32x4 g0 = *(const f32x4*)(g + col0 + bj * 128), g1 = *(const f32x4*)(g + col0 + bj * 128 + 4), b0 = *(const f32x4*)(b + col0 + bj * 128), b1 = *(const f32x4*)(b + col0 + bj * 128 + 4);
;                     float o[8];
; #pragma unroll
;                     for (int k = 0; k < 8; ++k) { const float gg = k < 4 ? g0[k & 3] : g1[k & 3], bb = k < 4 ? b0[k & 3] : b1[k & 3]; const float x1 = (p[k] - mu) * rstd * gg + bb; o[k] = x1 * ALPHA + acc[ai][bj][m][k >> 2][k & 3]; }
;                     if (out32) { *(f32x4*)(out32 + off + bj * 128) = (f32x4){o[0], o[1], o[2], o[3]}; *(f32x4*)(out32 + off + bj * 128 + 4) = (f32x4){o[4], o[5], o[6], o[7]}; }
;                     else *(u32x4*)(XBout + off + bj * 128) = pack8(o); }
.LBB0_2017:
	s_nop 0
	v_add_u32_e32 v34, 0xa0, v146
	v_ashrrev_i32_e32 v35, 31, v34
	v_lshlrev_b64 v[36:37], 10, v[34:35]
	v_lshlrev_b64 v[34:35], 7, v[34:35]
	v_lshl_add_u64 v[34:35], s[36:37], 0, v[34:35]
	v_lshl_add_u64 v[38:39], v[144:145], 2, v[34:35]
	s_nop 1
	v_mov_b32_e32 v42, v220
	v_mov_b32_e32 v43, v221
	v_mov_b32_e32 v44, v222
	v_mov_b32_e32 v45, v223
	v_mov_b32_e32 v46, v224
	v_mov_b32_e32 v47, v225
	v_mov_b32_e32 v48, v226
	v_mov_b32_e32 v49, v227
	v_mov_b32_e32 v50, v228
	v_mov_b32_e32 v51, v229
	v_mov_b32_e32 v52, v230
	v_mov_b32_e32 v53, v231
	v_mov_b32_e32 v54, v232
	v_mov_b32_e32 v55, v233
	v_mov_b32_e32 v56, v234
	v_mov_b32_e32 v57, v235
	v_lshl_add_u64 v[40:41], v[36:37], 0, v[148:149]
	global_load_dwordx4 v[34:37], v[38:39], off offset:16
	global_load_dwordx4 v[58:61], v[38:39], off
	v_lshl_add_u64 v[178:179], v[40:41], 1, s[26:27]
	global_load_dwordx4 v[170:173], v[178:179], off
	global_load_dwordx4 v[174:177], v[178:179], off offset:256
	s_mov_b32 s2, 0x3a800000
	s_and_b64 vcc, exec, s[18:19]
	s_waitcnt vmcnt(3)
	v_pk_add_f32 v[34:35], v[34:35], v[36:37]
	s_waitcnt vmcnt(2)
	v_pk_add_f32 v[38:39], v[58:59], v[60:61]
	s_nop 0
	v_pk_add_f32 v[34:35], v[38:39], v[34:35]
	ds_bpermute_b32 v36, v163, v34
	ds_bpermute_b32 v37, v163, v35
	s_waitcnt lgkmcnt(0)
	v_pk_add_f32 v[34:35], v[34:35], v[36:37]
	ds_bpermute_b32 v36, v162, v34
	ds_bpermute_b32 v37, v162, v35
	s_waitcnt lgkmcnt(0)
	v_pk_add_f32 v[34:35], v[34:35], v[36:37]
	s_nop 0
	v_pk_mul_f32 v[36:37], v[34:35], s[2:3] op_sel_hi:[1,0]
	s_nop 0
	v_fma_f32 v34, -v36, v36, v37
	v_max_f32_e32 v34, 0, v34
	v_add_f32_e32 v34, 0x3727c5ac, v34
	v_rsq_f32_e32 v38, v34
	v_lshl_add_u64 v[34:35], v[40:41], 1, s[26:27]
	s_waitcnt vmcnt(0)
	v_mov_b32_e32 v58, v170
	v_mov_b32_e32 v59, v171
	v_mov_b32_e32 v60, v172
	v_mov_b32_e32 v61, v173
	v_lshl_add_u64 v[40:41], v[40:41], 2, s[28:29]
	s_waitcnt vmcnt(0)
	v_lshlrev_b32_e32 v62, 16, v58
	v_and_b32_e32 v63, 0xffff0000, v58
	v_pk_add_f32 v[62:63], v[62:63], v[36:37] op_sel_hi:[1,0] neg_lo:[0,1] neg_hi:[0,1]
	s_nop 0
	v_pk_mul_f32 v[62:63], v[62:63], v[38:39] op_sel_hi:[1,0]
	s_nop 0
	v_pk_fma_f32 v[46:47], v[46:47], v[62:63], v[54:55]
	s_nop 0
	v_pk_fma_f32 v[30:31], v[46:47], s[86:87], v[30:31] op_sel_hi:[1,0,1]
	v_lshlrev_b32_e32 v46, 16, v59
	v_and_b32_e32 v47, 0xffff0000, v59
	v_pk_add_f32 v[46:47], v[46:47], v[36:37] op_sel_hi:[1,0] neg_lo:[0,1] neg_hi:[0,1]
	s_nop 0
	v_pk_mul_f32 v[46:47], v[46:47], v[38:39] op_sel_hi:[1,0]
	s_nop 0
	v_pk_fma_f32 v[46:47], v[48:49], v[46:47], v[56:57]
	s_nop 0
	v_pk_fma_f32 v[32:33], v[46:47], s[86:87], v[32:33] op_sel_hi:[1,0,1]
	v_lshlrev_b32_e32 v46, 16, v60
	v_and_b32_e32 v47, 0xffff0000, v60
	v_pk_add_f32 v[46:47], v[46:47], v[36:37] op_sel_hi:[1,0] neg_lo:[0,1] neg_hi:[0,1]
	s_nop 0
	v_pk_mul_f32 v[46:47], v[46:47], v[38:39] op_sel_hi:[1,0]
	s_nop 0
	v_pk_fma_f32 v[42:43], v[42:43], v[46:47], v[50:51]
	s_nop 0
	v_pk_fma_f32 v[26:27], v[42:43], s[86:87], v[26:27] op_sel_hi:[1,0,1]
	v_lshlrev_b32_e32 v42, 16, v61
	v_and_b32_e32 v43, 0xffff0000, v61
	v_pk_add_f32 v[42:43], v[42:43], v[36:37] op_sel_hi:[1,0] neg_lo:[0,1] neg_hi:[0,1]
	s_nop 0
	v_pk_mul_f32 v[42:43], v[42:43], v[38:39] op_sel_hi:[1,0]
	s_nop 0
	v_pk_fma_f32 v[42:43], v[44:45], v[42:43], v[52:53]
	s_nop 0
	v_pk_fma_f32 v[28:29], v[42:43], s[86:87], v[28:29] op_sel_hi:[1,0,1]
	s_cbranch_vccnz .LBB0_2043
	global_store_dwordx4 v[40:41], v[30:33], off
	global_store_dwordx4 v[40:41], v[26:29], off offset:16
	s_cbranch_execnz .LBB0_2020

; DI u32x4 pack8(const float (&v)[8]) { u32x4 w; w.x = pk2(v[0], v[1]); w.y = pk2(v[2], v[3]); w.z = pk2(v[4], v[5]); w.w = pk2(v[6], v[7]); return w; }
;     DI void operator()(const f32x4 (&acc)[2][2][4][2], const pg8::Unit& u, int wr, int wc, int fr, int fq) const {
;     ...
;                 for (int bj = 0; bj < 2; ++bj) { float p[8]; unpack8(*(const u32x4*)(XBin + off + bj * 128), p);
;                     const f32x4 g0 = *(const f32x4*)(g + col0 + bj * 128), g1 = *(const f32x4*)(g + col0 + bj * 128 + 4), b0 = *(const f32x4*)(b + col0 + bj * 128), b1 = *(const f32x4*)(b + col0 + bj * 128 + 4);
;                     float o[8];
; #pragma unroll
;                     for (int k = 0; k < 8; ++k) { const float gg = k < 4 ? g0[k & 3] : g1[k & 3], bb = k < 4 ? b0[k & 3] : b1[k & 3]; const float x1 = (p[k] - mu) * rstd * gg + bb; o[k] = x1 * ALPHA + acc[ai][bj][m][k >> 2][k & 3]; }
;                     if (out32) { *(f32x4*)(out32 + off + bj * 128) = (f32x4){o[0], o[1], o[2], o[3]}; *(f32x4*)(out32 + off + bj * 128 + 4) = (f32x4){o[4], o[5], o[6], o[7]}; }
;                     else *(u32x4*)(XBout + off + bj * 128) = pack8(o); }
.LBB0_2020:
	s_nop 1
	v_mov_b32_e32 v26, v174
	v_mov_b32_e32 v27, v175
	v_mov_b32_e32 v28, v176
	v_mov_b32_e32 v29, v177
	s_nop 0
	s_nop 1
	v_mov_b32_e32 v30, v242
	v_mov_b32_e32 v31, v243
	v_mov_b32_e32 v32, v244
	v_mov_b32_e32 v33, v245
	v_mov_b32_e32 v42, v246
	v_mov_b32_e32 v43, v247
	v_mov_b32_e32 v44, v248
	v_mov_b32_e32 v45, v249
	v_mov_b32_e32 v46, v250
	v_mov_b32_e32 v47, v251
	v_mov_b32_e32 v48, v252
	v_mov_b32_e32 v49, v253
	v_mov_b32_e32 v50, v186
	v_mov_b32_e32 v51, v187
	v_mov_b32_e32 v52, v196
	v_mov_b32_e32 v53, v197
	v_mov_b32_e32 v37, v36
	v_mov_b32_e32 v39, v38
	s_and_b64 vcc, exec, s[18:19]
	s_nop 0
	v_lshlrev_b32_e32 v54, 16, v26
	v_and_b32_e32 v55, 0xffff0000, v26
	v_lshlrev_b32_e32 v26, 16, v27
	v_and_b32_e32 v27, 0xffff0000, v27
	v_pk_add_f32 v[26:27], v[26:27], v[36:37] neg_lo:[0,1] neg_hi:[0,1]
	v_pk_add_f32 v[54:55], v[54:55], v[36:37] neg_lo:[0,1] neg_hi:[0,1]
	v_pk_mul_f32 v[26:27], v[38:39], v[26:27]
	v_pk_mul_f32 v[54:55], v[38:39], v[54:55]
	s_nop 0
	v_pk_fma_f32 v[26:27], v[44:45], v[26:27], v[52:53]
	v_pk_fma_f32 v[42:43], v[42:43], v[54:55], v[50:51]
	v_pk_fma_f32 v[24:25], v[26:27], s[86:87], v[24:25] op_sel_hi:[1,0,1]
	v_lshlrev_b32_e32 v26, 16, v28
	v_and_b32_e32 v27, 0xffff0000, v28
	v_pk_add_f32 v[26:27], v[26:27], v[36:37] neg_lo:[0,1] neg_hi:[0,1]
	v_pk_fma_f32 v[22:23], v[42:43], s[86:87], v[22:23] op_sel_hi:[1,0,1]
	v_pk_mul_f32 v[26:27], v[38:39], v[26:27]
	s_nop 0
	v_pk_fma_f32 v[26:27], v[30:31], v[26:27], v[46:47]
	s_nop 0
	v_pk_fma_f32 v[18:19], v[26:27], s[86:87], v[18:19] op_sel_hi:[1,0,1]
	v_lshlrev_b32_e32 v26, 16, v29
	v_and_b32_e32 v27, 0xffff0000, v29
	v_pk_add_f32 v[26:27], v[26:27], v[36:37] neg_lo:[0,1] neg_hi:[0,1]
	s_nop 0
	v_pk_mul_f32 v[26:27], v[38:39], v[26:27]
	s_nop 0
	v_pk_fma_f32 v[26:27], v[32:33], v[26:27], v[48:49]
	s_nop 0
	v_pk_fma_f32 v[20:21], v[26:27], s[86:87], v[20:21] op_sel_hi:[1,0,1]
	s_cbranch_vccnz .LBB0_2044
	global_store_dwordx4 v[40:41], v[22:25], off offset:512
	global_store_dwordx4 v[40:41], v[18:21], off offset:528
	s_cbranch_execnz .LBB0_2023

; DI float bperm(float v, int srclane) { return __int_as_float(__builtin_amdgcn_ds_bpermute(srclane << 2, __float_as_int(v))); }
; DI u32x4 pack8(const float (&v)[8]) { u32x4 w; w.x = pk2(v[0], v[1]); w.y = pk2(v[2], v[3]); w.z = pk2(v[4], v[5]); w.w = pk2(v[6], v[7]); return w; }
; DI void row_stats(const float* STAT, int row, int fq, int lane, float& mu, float& rstd) {
;     const f32x4 a = *(const f32x4*)(STAT + (size_t)row * 32 + fq * 8), b = *(const f32x4*)(STAT + (size_t)row * 32 + fq * 8 + 4);
;     float s = (a[0] + a[2]) + (b[0] + b[2]), q = (a[1] + a[3]) + (b[1] + b[3]);
;     s += bperm(s, lane ^ 16); q += bperm(q, lane ^ 16); s += bperm(s, lane ^ 32); q += bperm(q, lane ^ 32);
;     mu = s * (1.0f / 1024.0f); rstd = __builtin_amdgcn_rsqf(fmaxf(q * (1.0f / 1024.0f) - mu * mu, 0.f) + EPS);
;     DI void operator()(const f32x4 (&acc)[2][2][4][2], const pg8::Unit& u, int wr, int wc, int fr, int fq) const {
;     ...
;             for (int m = 0; m < 4; ++m) { const int row = row0 + ai * 128 + m * 16; const size_t off = (size_t)row * DMODEL + col0; float mu, rstd; row_stats(STAT, row, fq, lane, mu, rstd);
; #pragma unroll
;                 for (int bj = 0; bj < 2; ++bj) { float p[8]; unpack8(*(const u32x4*)(XBin + off + bj * 128), p);
;                     const f32x4 g0 = *(const f32x4*)(g + col0 + bj * 128), g1 = *(const f32x4*)(g + col0 + bj * 128 + 4), b0 = *(const f32x4*)(b + col0 + bj * 128), b1 = *(const f32x4*)(b + col0 + bj * 128 + 4);
;                     float o[8];
; #pragma unroll
;                     for (int k = 0; k < 8; ++k) { const float gg = k < 4 ? g0[k & 3] : g1[k & 3], bb = k < 4 ? b0[k & 3] : b1[k & 3]; const float x1 = (p[k] - mu) * rstd * gg + bb; o[k] = x1 * ALPHA + acc[ai][bj][m][k >> 2][k & 3]; }
;                     if (out32) { *(f32x4*)(out32 + off + bj * 128) = (f32x4){o[0], o[1], o[2], o[3]}; *(f32x4*)(out32 + off + bj * 128 + 4) = (f32x4){o[4], o[5], o[6], o[7]}; }
;                     else *(u32x4*)(XBout + off + bj * 128) = pack8(o); }
.LBB0_2023:
	s_nop 0
	v_add_u32_e32 v18, 0xb0, v146
	v_ashrrev_i32_e32 v19, 31, v18
	v_lshlrev_b64 v[20:21], 10, v[18:19]
	v_lshlrev_b64 v[18:19], 7, v[18:19]
	v_lshl_add_u64 v[18:19], s[36:37], 0, v[18:19]
	v_lshl_add_u64 v[22:23], v[144:145], 2, v[18:19]
	s_nop 1
	v_mov_b32_e32 v26, v220
	v_mov_b32_e32 v27, v221
	v_mov_b32_e32 v28, v222
	v_mov_b32_e32 v29, v223
	v_mov_b32_e32 v30, v224
	v_mov_b32_e32 v31, v225
	v_mov_b32_e32 v32, v226
	v_mov_b32_e32 v33, v227
	v_mov_b32_e32 v34, v228
	v_mov_b32_e32 v35, v229
	v_mov_b32_e32 v36, v230
	v_mov_b32_e32 v37, v231
	v_mov_b32_e32 v38, v232
	v_mov_b32_e32 v39, v233
	v_mov_b32_e32 v40, v234
	v_mov_b32_e32 v41, v235
	v_lshl_add_u64 v[24:25], v[20:21], 0, v[148:149]
	global_load_dwordx4 v[18:21], v[22:23], off offset:16
	global_load_dwordx4 v[42:45], v[22:23], off
	v_lshl_add_u64 v[178:179], v[24:25], 1, s[26:27]
	global_load_dwordx4 v[170:173], v[178:179], off
	global_load_dwordx4 v[174:177], v[178:179], off offset:256
	s_mov_b32 s2, 0x3a800000
	s_and_b64 vcc, exec, s[18:19]
	s_waitcnt vmcnt(3)
	v_pk_add_f32 v[18:19], v[18:19], v[20:21]
	s_waitcnt vmcnt(2)
	v_pk_add_f32 v[22:23], v[42:43], v[44:45]
	s_nop 0
	v_pk_add_f32 v[18:19], v[22:23], v[18:19]
	ds_bpermute_b32 v20, v163, v18
	ds_bpermute_b32 v21, v163, v19
	s_waitcnt lgkmcnt(0)
	v_pk_add_f32 v[18:19], v[18:19], v[20:21]
	ds_bpermute_b32 v20, v162, v18
	ds_bpermute_b32 v21, v162, v19
	s_waitcnt lgkmcnt(0)
	v_pk_add_f32 v[18:19], v[18:19], v[20:21]
	s_nop 0
	v_pk_mul_f32 v[20:21], v[18:19], s[2:3] op_sel_hi:[1,0]
	s_nop 0
	v_fma_f32 v18, -v20, v20, v21
	v_max_f32_e32 v18, 0, v18
	v_add_f32_e32 v18, 0x3727c5ac, v18
	v_rsq_f32_e32 v22, v18
	v_lshl_add_u64 v[18:19], v[24:25], 1, s[26:27]
	s_waitcnt vmcnt(0)
	v_mov_b32_e32 v42, v170
	v_mov_b32_e32 v43, v171
	v_mov_b32_e32 v44, v172
	v_mov_b32_e32 v45, v173
	v_lshl_add_u64 v[24:25], v[24:25], 2, s[28:29]
	s_waitcnt vmcnt(0)
	v_lshlrev_b32_e32 v46, 16, v42
	v_and_b32_e32 v47, 0xffff0000, v42
	v_pk_add_f32 v[46:47], v[46:47], v[20:21] op_sel_hi:[1,0] neg_lo:[0,1] neg_hi:[0,1]
	s_nop 0
	v_pk_mul_f32 v[46:47], v[46:47], v[22:23] op_sel_hi:[1,0]
	s_nop 0
	v_pk_fma_f32 v[30:31], v[30:31], v[46:47], v[38:39]
	s_nop 0
	v_pk_fma_f32 v[14:15], v[30:31], s[86:87], v[14:15] op_sel_hi:[1,0,1]
	v_lshlrev_b32_e32 v30, 16, v43
	v_and_b32_e32 v31, 0xffff0000, v43
	v_pk_add_f32 v[30:31], v[30:31], v[20:21] op_sel_hi:[1,0] neg_lo:[0,1] neg_hi:[0,1]
	s_nop 0
	v_pk_mul_f32 v[30:31], v[30:31], v[22:23] op_sel_hi:[1,0]
	s_nop 0
	v_pk_fma_f32 v[30:31], v[32:33], v[30:31], v[40:41]
	s_nop 0
	v_pk_fma_f32 v[16:17], v[30:31], s[86:87], v[16:17] op_sel_hi:[1,0,1]
	v_lshlrev_b32_e32 v30, 16, v44
	v_and_b32_e32 v31, 0xffff0000, v44
	v_pk_add_f32 v[30:31], v[30:31], v[20:21] op_sel_hi:[1,0] neg_lo:[0,1] neg_hi:[0,1]
	s_nop 0
	v_pk_mul_f32 v[30:31], v[30:31], v[22:23] op_sel_hi:[1,0]
	s_nop 0
	v_pk_fma_f32 v[26:27], v[26:27], v[30:31], v[34:35]
	s_nop 0
	v_pk_fma_f32 v[10:11], v[26:27], s[86:87], v[10:11] op_sel_hi:[1,0,1]
	v_lshlrev_b32_e32 v26, 16, v45
	v_and_b32_e32 v27, 0xffff0000, v45
	v_pk_add_f32 v[26:27], v[26:27], v[20:21] op_sel_hi:[1,0] neg_lo:[0,1] neg_hi:[0,1]
	s_nop 0
	v_pk_mul_f32 v[26:27], v[26:27], v[22:23] op_sel_hi:[1,0]
	s_nop 0
	v_pk_fma_f32 v[26:27], v[28:29], v[26:27], v[36:37]
	s_nop 0
	v_pk_fma_f32 v[12:13], v[26:27], s[86:87], v[12:13] op_sel_hi:[1,0,1]
	s_cbranch_vccnz .LBB0_2045
	global_store_dwordx4 v[24:25], v[14:17], off
	global_store_dwordx4 v[24:25], v[10:13], off offset:16
	s_cbranch_execnz .LBB0_2026

; DI u32x4 pack8(const float (&v)[8]) { u32x4 w; w.x = pk2(v[0], v[1]); w.y = pk2(v[2], v[3]); w.z = pk2(v[4], v[5]); w.w = pk2(v[6], v[7]); return w; }
;     DI void operator()(const f32x4 (&acc)[2][2][4][2], const pg8::Unit& u, int wr, int wc, int fr, int fq) const {
;     ...
;                 for (int bj = 0; bj < 2; ++bj) { float p[8]; unpack8(*(const u32x4*)(XBin + off + bj * 128), p);
;                     const f32x4 g0 = *(const f32x4*)(g + col0 + bj * 128), g1 = *(const f32x4*)(g + col0 + bj * 128 + 4), b0 = *(const f32x4*)(b + col0 + bj * 128), b1 = *(const f32x4*)(b + col0 + bj * 128 + 4);
;                     float o[8];
; #pragma unroll
;                     for (int k = 0; k < 8; ++k) { const float gg = k < 4 ? g0[k & 3] : g1[k & 3], bb = k < 4 ? b0[k & 3] : b1[k & 3]; const float x1 = (p[k] - mu) * rstd * gg + bb; o[k] = x1 * ALPHA + acc[ai][bj][m][k >> 2][k & 3]; }
;                     if (out32) { *(f32x4*)(out32 + off + bj * 128) = (f32x4){o[0], o[1], o[2], o[3]}; *(f32x4*)(out32 + off + bj * 128 + 4) = (f32x4){o[4], o[5], o[6], o[7]}; }
;                     else *(u32x4*)(XBout + off + bj * 128) = pack8(o); }
.LBB0_2026:
	s_nop 1
	v_mov_b32_e32 v10, v174
	v_mov_b32_e32 v11, v175
	v_mov_b32_e32 v12, v176
	v_mov_b32_e32 v13, v177
	s_nop 0
	s_nop 1
	v_mov_b32_e32 v14, v242
	v_mov_b32_e32 v15, v243
	v_mov_b32_e32 v16, v244
	v_mov_b32_e32 v17, v245
	v_mov_b32_e32 v26, v246
	v_mov_b32_e32 v27, v247
	v_mov_b32_e32 v28, v248
	v_mov_b32_e32 v29, v249
	v_mov_b32_e32 v30, v250
	v_mov_b32_e32 v31, v251
	v_mov_b32_e32 v32, v252
	v_mov_b32_e32 v33, v253
	v_mov_b32_e32 v34, v186
	v_mov_b32_e32 v35, v187
	v_mov_b32_e32 v36, v196
	v_mov_b32_e32 v37, v197
	v_mov_b32_e32 v21, v20
	v_mov_b32_e32 v23, v22
	s_and_b64 vcc, exec, s[18:19]
	s_nop 0
	v_lshlrev_b32_e32 v38, 16, v10
	v_and_b32_e32 v39, 0xffff0000, v10
	v_lshlrev_b32_e32 v10, 16, v11
	v_and_b32_e32 v11, 0xffff0000, v11
	v_pk_add_f32 v[10:11], v[10:11], v[20:21] neg_lo:[0,1] neg_hi:[0,1]
	v_pk_add_f32 v[38:39], v[38:39], v[20:21] neg_lo:[0,1] neg_hi:[0,1]
	v_pk_mul_f32 v[10:11], v[22:23], v[10:11]
	v_pk_mul_f32 v[38:39], v[22:23], v[38:39]
	s_nop 0
	v_pk_fma_f32 v[10:11], v[28:29], v[10:11], v[36:37]
	v_pk_fma_f32 v[26:27], v[26:27], v[38:39], v[34:35]
	v_pk_fma_f32 v[8:9], v[10:11], s[86:87], v[8:9] op_sel_hi:[1,0,1]
	v_lshlrev_b32_e32 v10, 16, v12
	v_and_b32_e32 v11, 0xffff0000, v12
	v_pk_add_f32 v[10:11], v[10:11], v[20:21] neg_lo:[0,1] neg_hi:[0,1]
	v_pk_fma_f32 v[6:7], v[26:27], s[86:87], v[6:7] op_sel_hi:[1,0,1]
	v_pk_mul_f32 v[10:11], v[22:23], v[10:11]
	s_nop 0
	v_pk_fma_f32 v[10:11], v[14:15], v[10:11], v[30:31]
	s_nop 0
	v_pk_fma_f32 v[2:3], v[10:11], s[86:87], v[2:3] op_sel_hi:[1,0,1]
	v_lshlrev_b32_e32 v10, 16, v13
	v_and_b32_e32 v11, 0xffff0000, v13
	v_pk_add_f32 v[10:11], v[10:11], v[20:21] neg_lo:[0,1] neg_hi:[0,1]
	s_nop 0
	v_pk_mul_f32 v[10:11], v[22:23], v[10:11]
	s_nop 0
	v_pk_fma_f32 v[10:11], v[16:17], v[10:11], v[32:33]
	s_nop 0
	v_pk_fma_f32 v[4:5], v[10:11], s[86:87], v[4:5] op_sel_hi:[1,0,1]
	s_cbranch_vccnz .LBB0_2046
	global_store_dwordx4 v[24:25], v[6:9], off offset:512
	global_store_dwordx4 v[24:25], v[2:5], off offset:528
	s_cbranch_execnz .LBB0_2029
